# s10 with p1_perm instead of rot0: P1 column order permuted so the 6-tile workgroups get q/k, v, mem-q, Fourier + one gate tile and the 5-tile workgroups the other ten gate columns
# baseline (speedup 1.0000x reference)
.LBB0_103:
	s_cmp_lt_i32 s82, 2
	s_cselect_b64 s[4:5], -1, 0
	s_add_u32 s6, s80, 0x1100000
	v_writelane_b32 v255, s84, 25
	s_addc_u32 s7, s81, 0
	v_writelane_b32 v255, s6, 26
	s_nop 1
	v_writelane_b32 v255, s7, 27
	s_add_u32 s6, s80, 0x1300000
	s_addc_u32 s7, s81, 0
	v_writelane_b32 v255, s6, 28
	s_nop 1
	v_writelane_b32 v255, s7, 29
	s_add_u32 s6, s80, 0x1b00000
	s_addc_u32 s7, s81, 0
	s_add_u32 s69, s80, 0x2600000
	v_writelane_b32 v255, s6, 30
	s_addc_u32 s70, s81, 0
	s_nop 0
	v_writelane_b32 v255, s7, 31
	s_add_u32 s6, s80, 0x2c00000
	s_addc_u32 s7, s81, 0
	s_add_u32 s60, s80, 0x8c00000
	s_addc_u32 s61, s81, 0
	s_add_u32 s96, s80, 0xdc00000
	s_addc_u32 s91, s81, 0
	s_add_u32 s62, s80, 0x7c00000
	v_writelane_b32 v255, s6, 32
	s_addc_u32 s63, s81, 0
	s_and_b64 s[28:29], s[4:5], s[0:1]
	v_writelane_b32 v255, s7, 33
	s_andn2_b64 vcc, exec, s[28:29]
	s_cbranch_vccnz .LBB0_220
	s_cmpk_lt_i32 s2, 0x590
	s_cselect_b64 s[4:5], -1, 0
	s_cmpk_gt_i32 s2, 0x58f
	v_readfirstlane_b32 s6, v216
	s_cbranch_scc1 .LBB0_107
	s_cmpk_gt_i32 s2, 0x57f
	s_cbranch_scc1 .LBB0_108
	s_ashr_i32 s0, s2, 31
	s_lshr_b32 s0, s0, 29
	s_add_i32 s0, s2, s0
	s_ashr_i32 s1, s0, 3
	s_and_b32 s0, s0, -8
	s_sub_i32 s0, s2, s0
	s_cmp_lt_i32 s0, 0
	s_movk_i32 s7, 0xb1
	s_cselect_b32 s7, s7, 0xb0
	s_mul_i32 s0, s0, s7
	s_add_i32 s0, s0, s1
	s_mul_hi_i32 s1, s0, 0x2e8ba2e9
	s_lshr_b32 s7, s1, 31
	s_ashr_i32 s1, s1, 5
	s_add_i32 s1, s1, s7
	s_lshl_b32 s7, s1, 3
	s_mulk_i32 s1, 0xb0
	s_sub_i32 s0, s0, s1
	s_sext_i32_i16 s1, s0
	s_bfe_u32 s1, s1, 0x3001c
	s_add_i32 s1, s0, s1
	s_bfe_u32 s8, s1, 0xd0003
	s_and_b32 s1, s1, 0xfff8
	s_sub_i32 s0, s0, s1
	s_sext_i32_i16 s0, s0
	s_add_i32 s38, s7, s0
	s_lshr_b32 s0, s8, 2
	s_and_b32 s1, s8, 3
	s_lshl_b32 s1, s1, 3
	s_mov_b32 s8, 0xb0a
	s_cmp_eq_u32 s0, 4
	s_cselect_b32 s8, 0x15140706, s8
	s_cmp_eq_u32 s0, 3
	s_cselect_b32 s8, 0x13120908, s8
	s_cmp_eq_u32 s0, 2
	s_cselect_b32 s8, 0x11100504, s8
	s_cmp_eq_u32 s0, 1
	s_cselect_b32 s8, 0xf0e0302, s8
	s_cmp_eq_u32 s0, 0
	s_cselect_b32 s8, 0xd0c0100, s8
	s_lshr_b32 s8, s8, s1
	s_and_b32 s8, s8, 0xff
	s_bfe_i32 s0, s8, 0x80000
	s_mul_i32 s0, s0, 0xffbb
	s_bfe_u32 s0, s0, 0x80008
	s_add_i32 s0, s0, s8
	s_bfe_i32 s1, s0, 0x80000
	s_and_b32 s1, 0xffff, s1
	s_lshr_b32 s1, s1, 4
	s_bfe_u32 s0, s0, 0x10007
	s_add_i32 s0, s1, s0
	s_mul_i32 s0, s0, 22
	s_sub_i32 s0, s8, s0
	s_mov_b32 s59, 0
	s_sext_i32_i8 s90, s0
	s_mov_b64 s[0:1], -1
	s_andn2_b64 vcc, exec, s[4:5]
	v_lshlrev_b32_e32 v16, 2, v216
	s_cbranch_vccz .LBB0_109
	s_branch .LBB0_178

.LBB0_117:
	s_andn2_b64 vcc, exec, s[12:13]
	s_mov_b32 s69, 1
	s_cbranch_vccnz .LBB0_119
	s_ashr_i32 s5, s4, 31
	s_lshr_b32 s5, s5, 29
	s_add_i32 s5, s4, s5
	s_ashr_i32 s12, s5, 3
	s_and_b32 s5, s5, -8
	s_sub_i32 s4, s4, s5
	s_cmp_lt_i32 s4, 0
	s_movk_i32 s5, 0xb1
	s_cselect_b32 s5, s5, 0xb0
	s_mul_i32 s4, s4, s5
	s_add_i32 s4, s4, s12
	s_mul_hi_i32 s5, s4, 0x2e8ba2e9
	s_lshr_b32 s12, s5, 31
	s_ashr_i32 s5, s5, 5
	s_add_i32 s5, s5, s12
	s_lshl_b32 s12, s5, 3
	s_sub_i32 s13, 64, s12
	s_min_i32 s13, s13, 8
	s_abs_i32 s14, s13
	v_cvt_f32_u32_e32 v0, s14
	s_sub_i32 s16, 0, s14
	s_mulk_i32 s5, 0xb0
	s_sub_i32 s4, s4, s5
	v_rcp_iflag_f32_e32 v0, v0
	s_abs_i32 s5, s4
	s_xor_b32 s15, s4, s13
	s_ashr_i32 s15, s15, 31
	v_mul_f32_e32 v0, 0x4f7ffffe, v0
	v_cvt_u32_f32_e32 v0, v0
	s_mov_b32 s69, 0
	v_readfirstlane_b32 s17, v0
	s_mul_i32 s16, s16, s17
	s_mul_hi_u32 s16, s17, s16
	s_add_i32 s17, s17, s16
	s_mul_hi_u32 s16, s5, s17
	s_mul_i32 s17, s16, s14
	s_sub_i32 s5, s5, s17
	s_add_i32 s17, s16, 1
	s_sub_i32 s18, s5, s14
	s_cmp_ge_u32 s5, s14
	s_cselect_b32 s16, s17, s16
	s_cselect_b32 s5, s18, s5
	s_add_i32 s17, s16, 1
	s_cmp_ge_u32 s5, s14
	s_cselect_b32 s5, s17, s16
	s_xor_b32 s5, s5, s15
	s_sub_i32 s5, s5, s15
	s_mul_i32 s13, s5, s13
	s_sub_i32 s4, s4, s13
	s_add_i32 s42, s12, s4
	s_lshr_b32 s4, s5, 2
	s_and_b32 s12, s5, 3
	s_lshl_b32 s12, s12, 3
	s_mov_b32 s5, 0xb0a
	s_cmp_eq_u32 s4, 4
	s_cselect_b32 s5, 0x15140706, s5
	s_cmp_eq_u32 s4, 3
	s_cselect_b32 s5, 0x13120908, s5
	s_cmp_eq_u32 s4, 2
	s_cselect_b32 s5, 0x11100504, s5
	s_cmp_eq_u32 s4, 1
	s_cselect_b32 s5, 0xf0e0302, s5
	s_cmp_eq_u32 s4, 0
	s_cselect_b32 s5, 0xd0c0100, s5
	s_lshr_b32 s5, s5, s12
	s_and_b32 s5, s5, 0xff
	s_sext_i32_i16 s4, s5
	s_mulk_i32 s4, 0xba3
	s_lshr_b32 s12, s4, 31
	s_lshr_b32 s4, s4, 16
	s_add_i32 s4, s4, s12
	s_mul_i32 s4, s4, 22
	s_sub_i32 s4, s5, s4
	s_sext_i32_i16 s44, s4
